# two idle slots: phase-1 slot converts out-proj, FFN up (both layers), FFN down layer 0, mLSTM in-proj; FFN-up-0 slot (workgroups 194..255) converts FFN down layer 1 and mLSTM out-proj
# speedup vs baseline: 1.0025x; 1.0025x over previous
; #define LAS __attribute__((address_space(3)))
; DI int ltid(int wv) { asm volatile("" : "+s"(wv)); int l = __builtin_amdgcn_mbcnt_hi(~0u, __builtin_amdgcn_mbcnt_lo(~0u, 0u)); asm volatile("" : "+v"(l)); return wv * 64 + l; }
; template <class F> DI void tr_items(const F& f, int Kdst, int Nrows, bf16_t* WT, LAS float* scr, int gw, int NGW, int lane, int& cum) {
;     const int nblk = Nrows / 32, nitems = (Kdst / 64) * nblk;
;     int first = (gw - cum) % NGW; if (first < 0) first += NGW; cum = (cum + nitems) % NGW;
;     for (int item = first; item < nitems; item += NGW) {
;         const int kb = item / nblk, nb = item % nblk, k0 = 64 * kb, n0 = 32 * nb;
; DI void phase_prologue(int wv, const ArgP a, LAS unsigned char* lds, int parts) {
;     unsigned char* ws = a.ws();
;     const int tid = ltid(wv), wave = tid >> 6, lane = tid & 63;
;     LAS float* scr = (LAS float*)(lds + wave * 8448);
;     const int gw = blockIdx.x * 8 + wave, NGW = gridDim.x * 8; int cum = 0;
;     if (parts & 1) {
;     { FW1 f{a.in(3), a.in(2)}; tr_items(f, 1024, 1536, (bf16_t*)(ws + O_W1T), scr, gw, NGW, lane, cum); }
.LBB0_15:
	s_mov_b32 s90, 0
	s_mov_b32 s91, 0
.Lpro_entry:
	s_cmp_eq_u32 s90, 0
	s_cselect_b64 s[94:95], -1, 0
	s_cmp_eq_u32 s90, 1
	s_cselect_b64 s[96:97], -1, 0
	s_cmp_eq_u32 s90, 2
	s_cselect_b64 s[98:99], -1, 0
	v_mbcnt_lo_u32_b32 v0, -1, 0
	s_lshr_b32 s50, s48, 6
	v_mbcnt_hi_u32_b32 v192, -1, v0
	s_mov_b64 s[2:3], s[82:83]
	s_mov_b32 s0, s50
	v_mov_b32_e32 v14, v192
	s_load_dwordx2 s[12:13], s[2:3], 0xe8
	s_load_dword s24, s[82:83], 0xf8
	s_lshl_b32 s46, s80, 3
	s_sub_i32 s46, s46, s91
	s_add_u32 s88, s82, 0xf8
	s_addc_u32 s89, s83, 0
	v_lshl_add_u32 v15, s0, 6, v14
	s_waitcnt lgkmcnt(0)
	s_lshl_b32 s14, s24, 3
	s_cmp_eq_u32 s90, 1
	s_cselect_b32 s14, 0x400, s14
	s_cmp_eq_u32 s90, 2
	s_cselect_b32 s14, 0x1f0, s14
	s_abs_i32 s15, s14
	v_cvt_f32_u32_e32 v1, s15
	v_ashrrev_i32_e32 v0, 6, v15
	s_movk_i32 s0, 0x2100
	v_mul_lo_u32 v2, v0, s0
	v_rcp_iflag_f32_e32 v3, v1
	v_add_u32_e32 v20, 0, v2
	s_sub_i32 s0, 0, s15
	v_add_u32_e32 v0, s46, v0
	v_mul_f32_e32 v2, 0x4f7ffffe, v3
	v_cvt_u32_f32_e32 v2, v2
	v_sub_u32_e32 v3, 0, v0
	v_max_i32_e32 v3, v0, v3
	v_ashrrev_i32_e32 v1, 31, v0
	v_readfirstlane_b32 s25, v2
	s_mul_i32 s0, s0, s25
	s_mul_hi_u32 s0, s25, s0
	s_add_i32 s25, s25, s0
	v_mul_hi_u32 v2, v3, s25
	v_mul_lo_u32 v2, v2, s15
	v_sub_u32_e32 v2, v3, v2
	v_subrev_u32_e32 v3, s15, v2
	v_cmp_le_u32_e32 vcc, s15, v2
	v_and_b32_e32 v16, 63, v14
	s_movk_i32 s0, 0x300
	v_cndmask_b32_e32 v2, v2, v3, vcc
	v_subrev_u32_e32 v3, s15, v2
	v_cmp_le_u32_e32 vcc, s15, v2
	s_mul_hi_u32 s16, s25, 0x300
	v_and_b32_e32 v18, 31, v14
	v_cndmask_b32_e32 v2, v2, v3, vcc
	v_xor_b32_e32 v2, v2, v1
	v_sub_u32_e32 v2, v2, v1
	v_ashrrev_i32_e32 v3, 31, v2
	v_and_b32_e32 v3, s14, v3
	v_add_u32_e32 v10, v3, v2
	v_cmp_gt_i32_e32 vcc, s0, v10
	v_lshrrev_b32_e32 v17, 5, v16
	v_lshrrev_b32_e32 v19, 3, v16
	v_lshlrev_b32_e32 v21, 3, v16
	s_and_b64 vcc, vcc, s[94:95]
	s_and_saveexec_b64 s[0:1], vcc
	s_cbranch_execz .LBB0_82
	s_load_dwordx4 s[4:7], s[2:3], 0x10
	v_lshrrev_b32_e32 v13, 3, v16
	v_and_b32_e32 v2, 56, v21
	v_and_b32_e32 v11, 31, v14
	v_lshrrev_b32_e32 v12, 5, v16
	v_mul_u32_u24_e32 v5, 0x84, v2
	v_lshlrev_b32_e32 v2, 1, v2
	v_mov_b32_e32 v3, 0
	v_lshlrev_b32_e32 v6, 2, v13
	v_lshl_add_u32 v4, v11, 2, v20
	v_lshl_add_u64 v[2:3], s[12:13], 0, v[2:3]
	s_mov_b64 s[8:9], 0x3e0b000
	v_add3_u32 v22, v20, v5, v6
	v_mul_u32_u24_e32 v5, 0x84, v12
	v_lshl_add_u64 v[2:3], v[2:3], 0, s[8:9]
	v_lshlrev_b32_e32 v23, 5, v10
	s_lshl_b32 s17, s14, 5
	s_mov_b64 s[8:9], 0
	s_mov_b32 s18, 0x2aaaaaab
	s_movk_i32 s19, 0xfa00
	s_movk_i32 s20, 0x5a0
	s_movk_i32 s21, 0x1680
	v_add_u32_e32 v24, v4, v5
	s_movk_i32 s22, 0x2ff
	s_branch .LBB0_18

; template <class F> DI void tr_items(const F& f, int Kdst, int Nrows, bf16_t* WT, LAS float* scr, int gw, int NGW, int lane, int& cum) {
;     const int nblk = Nrows / 32, nitems = (Kdst / 64) * nblk;
;     int first = (gw - cum) % NGW; if (first < 0) first += NGW; cum = (cum + nitems) % NGW;
;     for (int item = first; item < nitems; item += NGW) {
; DI void phase_prologue(int wv, const ArgP a, LAS unsigned char* lds, int parts) {
;     ...
;     { FWP f{a.in(15), 1024}; tr_items(f, 1024, 1024, (bf16_t*)(ws + O_WO1T), scr, gw, NGW, lane, cum); }
.LBB0_286:
	s_or_b64 exec, exec, s[0:1]
	s_mul_i32 s19, s19, s15
	s_sub_i32 s1, s18, s19
	s_ashr_i32 s0, s20, 31
	s_sub_i32 s4, s1, s15
	s_cmp_ge_u32 s1, s15
	s_cselect_b32 s1, s4, s1
	s_sub_i32 s4, s1, s15
	s_cmp_ge_u32 s1, s15
	s_cselect_b32 s1, s4, s1
	s_xor_b32 s1, s1, s0
	s_sub_i32 s8, s1, s0
	v_subrev_u32_e32 v2, s8, v0
	v_sub_u32_e32 v4, 0, v2
	v_ashrrev_i32_e32 v3, 31, v2
	v_max_i32_e32 v2, v2, v4
	v_mul_hi_u32 v4, v2, s25
	v_mul_lo_u32 v4, v4, s15
	v_sub_u32_e32 v2, v2, v4
	v_subrev_u32_e32 v4, s15, v2
	v_cmp_le_u32_e32 vcc, s15, v2
	s_movk_i32 s0, 0x1ff
	s_nop 0
	v_cndmask_b32_e32 v2, v2, v4, vcc
	v_subrev_u32_e32 v4, s15, v2
	v_cmp_le_u32_e32 vcc, s15, v2
	s_nop 1
	v_cndmask_b32_e32 v2, v2, v4, vcc
	v_xor_b32_e32 v2, v2, v3
	v_sub_u32_e32 v2, v2, v3
	v_ashrrev_i32_e32 v3, 31, v2
	v_and_b32_e32 v3, s14, v3
	v_add_u32_e32 v13, v3, v2
	v_cmp_lt_i32_e32 vcc, s0, v13
	s_orn2_b64 vcc, vcc, s[96:97]
	s_and_saveexec_b64 s[0:1], vcc
	s_xor_b64 s[0:1], exec, s[0:1]
	s_cbranch_execz .LBB0_288
	v_lshrrev_b32_e32 v17, 5, v16
	v_lshrrev_b32_e32 v19, 3, v16
	v_and_b32_e32 v2, 56, v21
	v_and_b32_e32 v18, 31, v14
	v_mul_u32_u24_e32 v8, 0x84, v2
	v_mov_b32_e32 v3, 0
	v_mul_u32_u24_e32 v9, 0x84, v17
	v_or_b32_e32 v10, 8, v19
	v_or_b32_e32 v11, 16, v19
	v_or_b32_e32 v12, 24, v19

; template <class F> DI void tr_items(const F& f, int Kdst, int Nrows, bf16_t* WT, LAS float* scr, int gw, int NGW, int lane, int& cum) {
;     const int nblk = Nrows / 32, nitems = (Kdst / 64) * nblk;
;     int first = (gw - cum) % NGW; if (first < 0) first += NGW; cum = (cum + nitems) % NGW;
;     for (int item = first; item < nitems; item += NGW) {
; DI void phase_prologue(int wv, const ArgP a, LAS unsigned char* lds, int parts) {
;     ...
;         { FWP f{a.in(26) + (size_t)l * 2816 * 1024, 1024}; tr_items(f, 2816, 1024, (bf16_t*)(ws + (l ? O_WDNT1 : O_WDNT0)), scr, gw, NGW, lane, cum); }
.LBB0_297:
	s_or_b64 exec, exec, s[16:17]
	s_add_i32 s0, s42, 0xb00
	s_ashr_i32 s16, s0, 31
	s_abs_i32 s0, s0
	s_mul_hi_u32 s17, s0, s25
	s_mul_i32 s17, s17, s15
	s_sub_i32 s0, s0, s17
	s_xor_b64 s[4:5], s[6:7], -1
	s_sub_i32 s17, s0, s15
	s_cmp_ge_u32 s0, s15
	s_cselect_b32 s0, s17, s0
	s_sub_i32 s17, s0, s15
	s_cmp_ge_u32 s0, s15
	s_cselect_b32 s0, s17, s0
	s_xor_b32 s0, s0, s16
	s_sub_i32 s20, s0, s16
	v_subrev_u32_e32 v4, s20, v0
	v_sub_u32_e32 v6, 0, v4
	v_ashrrev_i32_e32 v5, 31, v4
	v_max_i32_e32 v4, v4, v6
	v_mul_hi_u32 v6, v4, s25
	v_mul_lo_u32 v6, v6, s15
	v_sub_u32_e32 v4, v4, v6
	v_subrev_u32_e32 v6, s15, v4
	v_cmp_le_u32_e32 vcc, s15, v4
	s_nop 1
	v_cndmask_b32_e32 v4, v4, v6, vcc
	v_subrev_u32_e32 v6, s15, v4
	v_cmp_le_u32_e32 vcc, s15, v4
	s_nop 1
	v_cndmask_b32_e32 v4, v4, v6, vcc
	v_xor_b32_e32 v4, v4, v5
	v_sub_u32_e32 v4, v4, v5
	v_ashrrev_i32_e32 v5, 31, v4
	v_and_b32_e32 v5, s14, v5
	v_add_u32_e32 v8, v5, v4
	v_cmp_gt_i32_e32 vcc, s37, v8
	s_cmp_eq_u32 s43, 0
	s_cselect_b64 s[92:93], s[96:97], s[98:99]
	s_and_b64 vcc, vcc, s[92:93]
	s_and_saveexec_b64 s[16:17], vcc
	s_cbranch_execz .LBB0_293
	s_load_dwordx2 s[18:19], s[2:3], 0xd0
	s_mul_i32 s0, s43, 0xb00000
	v_mul_lo_u32 v34, v8, s39
	s_mul_i32 s21, s14, 0x16000
	v_lshl_add_u32 v35, v8, 5, v18
	s_waitcnt lgkmcnt(0)
	s_add_u32 s18, s18, s0
	s_addc_u32 s19, s19, 0
	s_and_b64 s[6:7], s[6:7], exec
	s_cselect_b32 s0, s38, 0xb00000
	v_lshl_add_u64 v[4:5], v[2:3], 0, s[0:1]
	s_mov_b64 s[6:7], 0

; template <class F> DI void tr_items(const F& f, int Kdst, int Nrows, bf16_t* WT, LAS float* scr, int gw, int NGW, int lane, int& cum) {
;     const int nblk = Nrows / 32, nitems = (Kdst / 64) * nblk;
;     int first = (gw - cum) % NGW; if (first < 0) first += NGW; cum = (cum + nitems) % NGW;
;     for (int item = first; item < nitems; item += NGW) {
; DI void phase_prologue(int wv, const ArgP a, LAS unsigned char* lds, int parts) {
;     ...
;     { FWP f{a.in(21), 1024}; tr_items(f, 1024, 1024, (bf16_t*)(ws + O_WO2T), scr, gw, NGW, lane, cum); }
.LBB0_303:
	s_or_b64 exec, exec, s[0:1]
	s_mul_i32 s11, s11, s15
	s_sub_i32 s1, s10, s11
	s_ashr_i32 s0, s16, 31
	s_sub_i32 s4, s1, s15
	s_cmp_ge_u32 s1, s15
	s_cselect_b32 s1, s4, s1
	s_sub_i32 s4, s1, s15
	s_cmp_ge_u32 s1, s15
	s_cselect_b32 s1, s4, s1
	s_xor_b32 s1, s1, s0
	s_sub_i32 s0, s0, s1
	v_add_u32_e32 v4, s0, v0
	v_sub_u32_e32 v6, 0, v4
	v_ashrrev_i32_e32 v5, 31, v4
	v_max_i32_e32 v4, v4, v6
	v_mul_hi_u32 v6, v4, s25
	v_mul_lo_u32 v6, v6, s15
	v_sub_u32_e32 v4, v4, v6
	v_subrev_u32_e32 v6, s15, v4
	v_cmp_le_u32_e32 vcc, s15, v4
	s_movk_i32 s0, 0x200
	s_nop 0
	v_cndmask_b32_e32 v4, v4, v6, vcc
	v_subrev_u32_e32 v6, s15, v4
	v_cmp_le_u32_e32 vcc, s15, v4
	s_nop 1
	v_cndmask_b32_e32 v4, v4, v6, vcc
	v_xor_b32_e32 v4, v4, v5
	v_sub_u32_e32 v4, v4, v5
	v_ashrrev_i32_e32 v5, 31, v4
	v_and_b32_e32 v5, s14, v5
	v_add_u32_e32 v6, v5, v4
	v_cmp_gt_i32_e32 vcc, s0, v6
	s_and_b64 vcc, vcc, s[98:99]
	s_and_saveexec_b64 s[0:1], vcc
	s_cbranch_execz .LBB0_306
	s_load_dwordx2 s[4:5], s[2:3], 0xa8
	s_mov_b64 s[6:7], 0x1680000
	v_lshl_add_u64 v[2:3], v[2:3], 0, s[6:7]
	v_lshlrev_b32_e32 v7, 5, v6
	s_mov_b64 s[6:7], 0
	s_movk_i32 s8, 0x1ff
	v_add_u32_e32 v8, 0x400, v20
	v_add_u32_e32 v9, 0x800, v20
	v_add_u32_e32 v24, 0xc00, v20
	v_add_u32_e32 v25, 0x1000, v20
	v_add_u32_e32 v26, 0x1400, v20
	v_add_u32_e32 v27, 0x1800, v20
	v_add_u32_e32 v28, 0x1c00, v20

; #define LAS __attribute__((address_space(3)))
; DI int ltid(int wv) { asm volatile("" : "+s"(wv)); int l = __builtin_amdgcn_mbcnt_hi(~0u, __builtin_amdgcn_mbcnt_lo(~0u, 0u)); asm volatile("" : "+v"(l)); return wv * 64 + l; }
; DI unsigned xb_xcc_id() { return (unsigned)__builtin_amdgcn_s_getreg((3 << 11) | 20) & 0xFu; }
; DI void xcd_barrier(int wv, unsigned* bar, volatile LAS unsigned* st) {
;     asm volatile("s_waitcnt vmcnt(0)" ::: "memory");
;     __syncthreads();
;     if (ltid(wv) == 0) {
;         const unsigned x = xb_xcc_id();
;         __builtin_amdgcn_s_waitcnt(0);
;         unsigned nloc = st[0], nx = st[1];
;         if (nloc == 0u) { xcd_barrier_complete(bar, x, nloc, nx); st[0] = nloc; st[1] = nx; }
.LBB0_316:
	s_or_b64 exec, exec, s[0:1]
	s_cmp_eq_u32 s90, 1
	s_cbranch_scc1 .Lslot_return
	s_cmp_eq_u32 s90, 2
	s_cbranch_scc1 .Ltramp_out
	s_mov_b64 s[2:3], s[82:83]
	s_mov_b32 s0, s50
	s_waitcnt vmcnt(0)
	s_waitcnt lgkmcnt(0)
	s_barrier
	s_lshl_b32 s0, s0, 6
	v_mov_b32_e32 v0, v192
	s_sub_i32 s0, 0, s0
	s_nop 0
	v_cmp_eq_u32_e32 vcc, s0, v0
	s_and_saveexec_b64 s[0:1], vcc
	s_xor_b64 s[0:1], exec, s[0:1]
	v_writelane_b32 v240, s50, 0
	s_cbranch_execz .LBB0_369
	s_add_i32 s5, 0, 0x22000
	v_mov_b32_e32 v0, s5
	s_load_dwordx2 s[2:3], s[2:3], 0xe8
	s_getreg_b32 s4, hwreg(HW_REG_XCC_ID, 0, 4)
	s_waitcnt vmcnt(0) expcnt(0) lgkmcnt(0)
	ds_read_b32 v2, v0
	s_add_i32 s5, 0, 0x22004
	v_mov_b32_e32 v0, s5
	ds_read_b32 v0, v0
	s_and_b32 s47, s4, 15
	s_waitcnt lgkmcnt(1)
	v_cmp_ne_u32_e32 vcc, 0, v2
	s_cbranch_vccnz .LBB0_332
	s_add_u32 s4, s2, 0x1d83200
	s_addc_u32 s5, s3, 0
	s_add_u32 s6, s2, 0x1d83400
	s_addc_u32 s7, s3, 0
	s_add_u32 s8, s2, 0x1d83500
	s_addc_u32 s9, s3, 0
	s_add_u32 s10, s2, 0x1d83600
	s_addc_u32 s11, s3, 0
	s_add_u32 s12, s2, 0x1d83700
	s_addc_u32 s13, s3, 0
	s_add_u32 s14, s2, 0x1d83800
	s_addc_u32 s15, s3, 0
	s_add_u32 s16, s2, 0x1d83900
	s_addc_u32 s17, s3, 0
	s_add_u32 s18, s2, 0x1d83a00
	s_addc_u32 s19, s3, 0
	s_add_u32 s20, s2, 0x1d83b00
	s_addc_u32 s21, s3, 0
	s_add_u32 s22, s2, 0x1d83c00
	s_addc_u32 s23, s3, 0
	s_add_u32 s24, s2, 0x1d83d00
	s_addc_u32 s25, s3, 0
	s_add_u32 s26, s2, 0x1d83e00
	s_addc_u32 s27, s3, 0
	s_add_u32 s28, s2, 0x1d83f00
	s_addc_u32 s29, s3, 0
	s_add_u32 s30, s2, 0x1d84000
	s_addc_u32 s31, s3, 0
	s_add_u32 s34, s2, 0x1d84100
	s_load_dword s49, s[88:89], 0x0
	s_addc_u32 s35, s3, 0
	s_add_u32 s36, s2, 0x1d84200
	s_addc_u32 s37, s3, 0
	s_add_u32 s38, s2, 0x1d84300
	s_addc_u32 s39, s3, 0
	s_mov_b32 s50, 1
	v_mov_b32_e32 v16, 0
	s_branch .LBB0_320

; #define WSB (getargs().ws())
; #define GSYNC() xcd_barrier(wv, BARW, BARST)
; __global__ void __launch_bounds__(512, 2) fwd_kernel(Args a_unused) {
;     ...
;       pg8::gemm_phase<false>(wv, lds, XBP, 1024, (const bf16_t*)(WSB + O_W1T), 1024, 1024, 64, 6, E); }
;     }
;     ...
;     GSYNC();
.LBB0_388:
	s_cmpk_lt_u32 s80, 0x80
	s_cbranch_scc1 .Lslot_skip
	s_barrier
	s_mov_b32 s90, 1
	s_movk_i32 s91, 0x400
	s_branch .Lpro_entry

; #define LAS __attribute__((address_space(3)))
; DI int ltid(int wv) { asm volatile("" : "+s"(wv)); int l = __builtin_amdgcn_mbcnt_hi(~0u, __builtin_amdgcn_mbcnt_lo(~0u, 0u)); asm volatile("" : "+v"(l)); return wv * 64 + l; }
; DI void phase_prologue(int wv, const ArgP a, LAS unsigned char* lds, int parts) {
;     unsigned char* ws = a.ws();
;     const int tid = ltid(wv), wave = tid >> 6, lane = tid & 63;
;     LAS float* scr = (LAS float*)(lds + wave * 8448);
;     const int gw = blockIdx.x * 8 + wave, NGW = gridDim.x * 8; int cum = 0;
.Ltramp_in:
	s_branch .Lpro_entry

; DI ArgP getargs() { ArgP r; r.p = (const __attribute__((address_space(4))) Args*)__builtin_amdgcn_kernarg_segment_ptr(); asm volatile("" : "+s"(r.p)); return r; }
; #define WSB (getargs().ws())
; #define GSYNC() xcd_barrier(wv, BARW, BARST)
; __global__ void __launch_bounds__(512, 2) fwd_kernel(Args a_unused) {
;     ...
;     { EpiUp E{(bf16_t*)(WSB + O_ACT), RSS + 1 * S, getargs().in(24), getargs().in(25), lds + 131072};
;       pg8::gemm_phase<true>(wv, lds, XBP, 1024, (const bf16_t*)(WSB + O_WUPT0), 1024, 1024, 67, 22, E); }
;     }
;     ...
;     GSYNC();
.LBB0_1126:
	s_cmpk_lt_u32 s80, 0xc2
	s_cbranch_scc1 .Lslot2_skip
	s_barrier
	v_mov_b32_e32 v238, v139
	v_mov_b32_e32 v239, v155
	v_readlane_b32 s48, v240, 0
	s_nop 0
	s_lshl_b32 s48, s48, 6
	s_mov_b32 s90, 2
	s_movk_i32 s91, 0x610
	s_branch .Ltramp_in
.Lslot2_return:
	v_mov_b32_e32 v139, v238
	v_mov_b32_e32 v155, v239
	s_lshl_b32 s46, s80, 3
